# FINAL-norm loop: the three later gain loads issued with the first one, counted vmcnt so stores are not waited inside the iteration
# baseline (speedup 1.0000x reference)
; DI int tidx() { int t = __builtin_amdgcn_workitem_id_x(); asm volatile("" : "+v"(t)); return t; }
; DI float bflo(unsigned u) { return __uint_as_float(u << 16); }
; DI float bfhi(unsigned u) { return __uint_as_float(u & 0xffff0000u); }
; DI float rstd16(const float* ssq, int m) {
;   float s = 0.f;
; #pragma unroll
;   for (int c = 0; c < 16; ++c) s += ssq[(size_t)c * TP + m];
;   return rsqrtf(s * (1.f / 1024.f) + RMS_EPS);
; }
; DI void final_rows(CP p, int item) {
;   const int lane = tidx() & 63, wv = tidx() >> 6;
;   const int orow = item * 8 + wv;
;   int r;
;   if (orow < 16384) { int s = orow >> 13; r = s * LPR + 16 + (orow & 8191); }
;   else { int x = orow - 16384; int s = x >> 11; r = 2 * LPR + s * LSM + 16 + (x & 2047); }
;   const float rs = rstd16(p.ssq, r);
;   const u16* src = p.hb + (size_t)r * 1024 + lane * 16;
;   uint4 a = *(const uint4*)src, b = *(const uint4*)(src + 8);
;   unsigned w[8] = {a.x, a.y, a.z, a.w, b.x, b.y, b.z, b.w};
;   float* dst = p.out + (size_t)orow * 1024 + lane * 16;
;   const float* gn = p.final_norm + lane * 16;
; #pragma unroll
;   for (int i = 0; i < 4; ++i) {
;     float4 o;
;     o.x = bflo(w[2 * i]) * rs * gn[4 * i]; o.y = bfhi(w[2 * i]) * rs * gn[4 * i + 1];
;     o.z = bflo(w[2 * i + 1]) * rs * gn[4 * i + 2]; o.w = bfhi(w[2 * i + 1]) * rs * gn[4 * i + 3];
;     *(float4*)(dst + 4 * i) = o;
;   }
; }
.LBB0_14:
	s_or_b64 exec, exec, s[8:9]
	s_load_dwordx2 s[8:9], s[0:1], 0x128
	v_and_b32_e32 v5, v5, v2
	v_add3_u32 v4, v5, v4, v3
	v_ashrrev_i32_e32 v5, 31, v4
	v_lshlrev_b32_e32 v0, 4, v0
	s_waitcnt lgkmcnt(0)
	v_lshl_add_u64 v[6:7], v[4:5], 2, s[8:9]
	s_waitcnt vmcnt(2)
	v_add_co_u32_e32 v8, vcc, 0x20000, v6
	v_lshlrev_b64 v[4:5], 11, v[4:5]
	s_nop 0
	v_addc_co_u32_e32 v9, vcc, 0, v7, vcc
	v_add_co_u32_e32 v10, vcc, 0x40000, v6
	s_add_i32 s14, s14, s94
	s_nop 0
	v_addc_co_u32_e32 v11, vcc, 0, v7, vcc
	v_add_co_u32_e32 v12, vcc, 0x60000, v6
	s_add_i32 s11, s11, s10
	s_nop 0
	v_addc_co_u32_e32 v13, vcc, 0, v7, vcc
	v_add_co_u32_e32 v14, vcc, 0x81000, v6
	s_cmpk_gt_i32 s14, 0xfff
	s_nop 0
	v_addc_co_u32_e32 v15, vcc, 0, v7, vcc
	s_waitcnt vmcnt(1)
	v_add_co_u32_e32 v16, vcc, 0xa1000, v6
	s_nop 1
	v_addc_co_u32_e32 v17, vcc, 0, v7, vcc
	v_add_co_u32_e32 v18, vcc, 0xc1000, v6
	s_nop 1
	v_addc_co_u32_e32 v19, vcc, 0, v7, vcc
	s_waitcnt vmcnt(0)
	v_add_co_u32_e32 v20, vcc, 0xe1000, v6
	s_nop 1
	v_addc_co_u32_e32 v21, vcc, 0, v7, vcc
	global_load_dword v3, v[6:7], off
	global_load_dword v22, v[8:9], off offset:1024
	global_load_dword v23, v[10:11], off offset:2048
	global_load_dword v24, v[12:13], off offset:3072
	global_load_dword v25, v[14:15], off
	global_load_dword v26, v[16:17], off offset:1024
	global_load_dword v27, v[18:19], off offset:2048
	global_load_dword v28, v[20:21], off offset:3072
	v_add_co_u32_e32 v8, vcc, 0x102000, v6
	s_waitcnt vmcnt(7)
	v_add_f32_e32 v3, 0, v3
	v_addc_co_u32_e32 v9, vcc, 0, v7, vcc
	v_add_co_u32_e32 v10, vcc, 0x122000, v6
	s_waitcnt vmcnt(6)
	v_add_f32_e32 v3, v3, v22
	v_addc_co_u32_e32 v11, vcc, 0, v7, vcc
	v_add_co_u32_e32 v12, vcc, 0x142000, v6
	s_waitcnt vmcnt(5)
	v_add_f32_e32 v3, v3, v23
	v_addc_co_u32_e32 v13, vcc, 0, v7, vcc
	v_add_co_u32_e32 v14, vcc, 0x162000, v6
	s_waitcnt vmcnt(4)
	v_add_f32_e32 v3, v3, v24
	v_addc_co_u32_e32 v15, vcc, 0, v7, vcc
	v_add_co_u32_e32 v16, vcc, 0x183000, v6
	s_waitcnt vmcnt(3)
	v_add_f32_e32 v3, v3, v25
	v_addc_co_u32_e32 v17, vcc, 0, v7, vcc
	v_add_co_u32_e32 v18, vcc, 0x1a3000, v6
	s_waitcnt vmcnt(2)
	v_add_f32_e32 v3, v3, v26
	v_addc_co_u32_e32 v19, vcc, 0, v7, vcc
	v_add_co_u32_e32 v20, vcc, 0x1c3000, v6
	s_waitcnt vmcnt(1)
	v_add_f32_e32 v3, v3, v27
	v_addc_co_u32_e32 v21, vcc, 0, v7, vcc
	v_add_co_u32_e32 v6, vcc, 0x1e3000, v6
	s_waitcnt vmcnt(0)
	v_add_f32_e32 v3, v3, v28
	v_addc_co_u32_e32 v7, vcc, 0, v7, vcc
	global_load_dword v29, v[8:9], off
	global_load_dword v30, v[10:11], off offset:1024
	global_load_dword v31, v[12:13], off offset:2048
	s_nop 0
	global_load_dword v14, v[14:15], off offset:3072
	s_nop 0
	global_load_dword v15, v[16:17], off
	s_nop 0
	global_load_dword v16, v[18:19], off offset:1024
	global_load_dword v17, v[20:21], off offset:2048
	s_nop 0
	global_load_dword v18, v[6:7], off offset:3072
	s_load_dwordx2 s[8:9], s[0:1], 0xf8
	v_and_b32_e32 v8, 0x3f0, v0
	v_lshlrev_b32_e32 v0, 1, v8
	s_waitcnt lgkmcnt(0)
	v_lshl_add_u64 v[4:5], s[8:9], 0, v[4:5]
	v_lshl_add_u64 v[12:13], v[4:5], 0, v[0:1]
	global_load_dwordx4 v[4:7], v[12:13], off
	v_lshlrev_b32_e32 v0, 2, v8
	global_load_dwordx4 v[8:11], v0, s[40:41]
	global_load_dwordx4 v[200:203], v0, s[40:41] offset:16
	global_load_dwordx4 v[204:207], v0, s[40:41] offset:32
	global_load_dwordx4 v[208:211], v0, s[40:41] offset:48
	s_mov_b32 s8, 0x800000
	s_waitcnt vmcnt(12)
	v_add_f32_e32 v3, v3, v29
	s_waitcnt vmcnt(11)
	v_add_f32_e32 v3, v3, v30
	s_waitcnt vmcnt(10)
	v_add_f32_e32 v3, v3, v31
	s_waitcnt vmcnt(9)
	v_add_f32_e32 v3, v3, v14
	s_waitcnt vmcnt(8)
	v_add_f32_e32 v3, v3, v15
	s_waitcnt vmcnt(7)
	v_add_f32_e32 v3, v3, v16
	s_waitcnt vmcnt(6)
	v_add_f32_e32 v3, v3, v17
	s_waitcnt vmcnt(5)
	v_add_f32_e32 v3, v3, v18
	v_fmamk_f32 v3, v3, 0x3a800000, v180
	v_mul_f32_e32 v14, 0x4b800000, v3
	v_cmp_gt_f32_e32 vcc, s8, v3
	s_nop 1
	v_cndmask_b32_e32 v3, v3, v14, vcc
	v_rsq_f32_e32 v3, v3
	global_load_dwordx4 v[12:15], v[12:13], off offset:16
	v_mul_f32_e32 v16, 0x45800000, v3
	v_cndmask_b32_e32 v16, v3, v16, vcc
	v_ashrrev_i32_e32 v3, 31, v2
	v_lshlrev_b64 v[2:3], 12, v[2:3]
	v_lshl_add_u64 v[2:3], s[42:43], 0, v[2:3]
	v_lshl_add_u64 v[18:19], v[2:3], 0, v[0:1]
	s_waitcnt vmcnt(5)
	v_lshlrev_b32_e32 v2, 16, v4
	v_and_b32_e32 v3, 0xffff0000, v4
	v_lshlrev_b32_e32 v4, 16, v5
	v_and_b32_e32 v5, 0xffff0000, v5
	v_pk_mul_f32 v[2:3], v[16:17], v[2:3] op_sel_hi:[0,1]
	v_pk_mul_f32 v[4:5], v[16:17], v[4:5] op_sel_hi:[0,1]
	s_waitcnt vmcnt(4)
	v_pk_mul_f32 v[2:3], v[2:3], v[8:9]
	v_pk_mul_f32 v[4:5], v[4:5], v[10:11]
	global_store_dwordx4 v[18:19], v[2:5], off
	v_lshlrev_b32_e32 v8, 16, v6
	v_and_b32_e32 v9, 0xffff0000, v6
	v_lshlrev_b32_e32 v6, 16, v7
	v_and_b32_e32 v7, 0xffff0000, v7
	v_pk_mul_f32 v[8:9], v[16:17], v[8:9] op_sel_hi:[0,1]
	v_pk_mul_f32 v[6:7], v[16:17], v[6:7] op_sel_hi:[0,1]
	s_waitcnt vmcnt(1)
	v_pk_mul_f32 v[2:3], v[8:9], v[200:201]
	v_pk_mul_f32 v[4:5], v[6:7], v[202:203]
	global_store_dwordx4 v[18:19], v[2:5], off offset:16
	v_lshlrev_b32_e32 v6, 16, v12
	v_and_b32_e32 v7, 0xffff0000, v12
	v_lshlrev_b32_e32 v8, 16, v13
	v_and_b32_e32 v9, 0xffff0000, v13
	v_pk_mul_f32 v[6:7], v[16:17], v[6:7] op_sel_hi:[0,1]
	v_pk_mul_f32 v[8:9], v[16:17], v[8:9] op_sel_hi:[0,1]
	s_waitcnt vmcnt(2)
	v_pk_mul_f32 v[2:3], v[6:7], v[204:205]
	v_pk_mul_f32 v[4:5], v[8:9], v[206:207]
	global_store_dwordx4 v[18:19], v[2:5], off offset:32
	v_lshlrev_b32_e32 v6, 16, v14
	v_and_b32_e32 v7, 0xffff0000, v14
	v_lshlrev_b32_e32 v8, 16, v15
	v_and_b32_e32 v9, 0xffff0000, v15
	v_pk_mul_f32 v[6:7], v[16:17], v[6:7] op_sel_hi:[0,1]
	v_pk_mul_f32 v[8:9], v[16:17], v[8:9] op_sel_hi:[0,1]
	s_waitcnt vmcnt(3)
	v_pk_mul_f32 v[2:3], v[6:7], v[208:209]
	v_pk_mul_f32 v[4:5], v[8:9], v[210:211]
	global_store_dwordx4 v[18:19], v[2:5], off offset:48
	s_cbranch_scc1 .LBB0_22
